# mix work queue partitioned per XCD (XCC_ID): each XCD pops its own ticket counter over a contiguous 1/8 slice of every item class so K/V-, line- and weight-sharing items share one L2
# speedup vs baseline: 1.0070x; 1.0070x over previous
.LBB0_633:
	s_or_b64 exec, exec, s[36:37]
	s_lshl_b32 s70, s14, 6
	s_lshl_b64 s[20:21], s[70:71], 2
	s_add_u32 s15, s30, s20
	s_addc_u32 s16, s31, s21
	s_add_u32 s20, s15, 0xf79f700
	s_waitcnt lgkmcnt(0)
	v_cvt_f32_u32_e32 v0, s14
	s_addc_u32 s21, s16, 0
	s_getreg_b32 s100, hwreg(HW_REG_XCC_ID, 0, 4)
	s_and_b32 s100, s100, 7
	s_lshl_b32 s101, s100, 5
	s_add_u32 s20, s20, s101
	s_addc_u32 s21, s21, 0
	v_writelane_b32 v254, s100, 0
	v_writelane_b32 v251, s20, 37
	v_writelane_b32 v253, s84, 10
	s_movk_i32 s15, 0xbc
	v_writelane_b32 v251, s21, 38
	s_and_b64 s[20:21], s[84:85], exec
	s_cselect_b32 s15, s15, 0x78
	s_lshl_b32 s16, s14, 16
	v_mul_f32_e32 v0, 0xbe99999a, v0
	v_writelane_b32 v251, s16, 39
	v_mul_f32_e32 v1, 0x3fb8aa3b, v0
	s_mov_b32 s16, 0x3fb8aa3b
	v_fma_f32 v2, v0, s16, -v1
	v_rndne_f32_e32 v3, v1
	v_fmac_f32_e32 v2, 0x32a5705f, v0
	v_sub_f32_e32 v1, v1, v3
	v_add_f32_e32 v1, v1, v2
	v_exp_f32_e32 v1, v1
	v_cvt_i32_f32_e32 v2, v3
	s_lshl_b32 s16, s14, 2
	v_writelane_b32 v251, s16, 40
	s_mov_b32 s16, 0xc2ce8ed0
	v_ldexp_f32 v1, v1, v2
	v_cmp_ngt_f32_e32 vcc, s16, v0
	s_mov_b32 s16, 0x42b17218
	s_lshl_b32 s38, s14, 9
	v_cndmask_b32_e32 v1, 0, v1, vcc
	v_cmp_nlt_f32_e32 vcc, s16, v0
	s_lshl_b32 s16, s14, 7
	v_writelane_b32 v251, s16, 41
	s_lshl_b32 s19, s14, 18
	v_writelane_b32 v251, s19, 42
	s_mov_b32 s40, s38
	v_writelane_b32 v253, s85, 11
	v_writelane_b32 v251, s40, 43
	s_mov_b32 s39, s71
	s_lshl_b32 s74, s14, 10
	v_writelane_b32 v251, s41, 44
	v_readlane_b32 s40, v253, 12
	s_lshl_b32 s70, s14, 8
	s_or_b32 s16, s74, 0x200
	s_lshl_b32 s36, s14, 6
	s_lshl_b64 s[38:39], s[38:39], 2
	v_readlane_b32 s48, v253, 20
	v_readlane_b32 s49, v253, 21
	s_add_u32 s19, s48, s38
	v_readlane_b32 s50, v253, 22
	v_writelane_b32 v251, s19, 45
	s_addc_u32 s19, s49, s39
	s_lshl_b64 s[38:39], s[70:71], 2
	s_mul_i32 s20, s14, 0x1200
	s_mov_b32 s21, s71
	v_readlane_b32 s51, v253, 23
	s_add_u32 s38, s50, s38
	v_readlane_b32 s54, v253, 26
	s_addc_u32 s39, s51, s39
	s_lshl_b64 s[20:21], s[20:21], 2
	s_mul_i32 s22, s14, 0x600
	s_mov_b32 s23, s71
	v_readlane_b32 s55, v253, 27
	s_add_u32 s80, s54, s20
	s_addc_u32 s81, s55, s21
	s_lshl_b64 s[20:21], s[22:23], 2
	s_mov_b32 s37, s71
	v_writelane_b32 v251, s19, 46
	s_add_u32 s82, s12, s20
	v_writelane_b32 v251, s38, 47
	s_addc_u32 s83, s13, s21
	s_lshl_b64 s[20:21], s[36:37], 2
	v_readlane_b32 s19, v252, 53
	v_writelane_b32 v251, s39, 48
	s_add_u32 s19, s19, s20
	v_writelane_b32 v251, s19, 49
	v_readlane_b32 s19, v252, 54
	s_addc_u32 s19, s19, s21
	s_add_u32 s17, s17, 0x1800000
	v_writelane_b32 v251, s19, 50
	v_writelane_b32 v251, s17, 51
	s_addc_u32 s17, s18, 0
	v_writelane_b32 v251, s17, 52
	v_readfirstlane_b32 s17, v188
	s_lshr_b32 s18, s17, 8
	s_mul_i32 s17, s18, 0x12000
	s_add_i32 s17, s17, 0
	v_writelane_b32 v251, s18, 53
	s_addk_i32 s18, 0xff80
	v_writelane_b32 v251, s18, 54
	s_add_i32 s18, s17, 0x8800
	v_writelane_b32 v251, s18, 55
	s_add_i32 s18, s17, 0x4400
	v_writelane_b32 v251, s18, 56
	s_add_i32 s18, s17, 0x800
	v_writelane_b32 v251, s18, 57
	s_mul_i32 s19, s14, 0x1a00000
	v_readlane_b32 s20, v251, 32
	s_add_u32 s19, s20, s19
	v_cndmask_b32_e32 v0, v200, v1, vcc
	v_writelane_b32 v251, s19, 58
	v_fmamk_f32 v150, v0, 0xbf19999a, v192
	s_mul_hi_u32 s18, s14, 0x1a00000
	v_readlane_b32 s19, v251, 33
	v_sub_f32_e32 v203, 1.0, v150
	s_mov_b32 s75, s71
	s_addc_u32 s18, s19, s18
	s_barrier
	v_readlane_b32 s41, v253, 13
	v_readlane_b32 s42, v253, 14
	v_readlane_b32 s43, v253, 15
	v_readlane_b32 s44, v253, 16
	v_readlane_b32 s45, v253, 17
	v_readlane_b32 s46, v253, 18
	v_readlane_b32 s47, v253, 19
	v_readlane_b32 s52, v253, 24
	v_readlane_b32 s53, v253, 25
	v_writelane_b32 v251, s18, 59
	s_branch .LBB0_637

.LBB0_641:
	s_or_b64 exec, exec, s[36:37]
	v_mov_b32_e32 v0, s1
	s_waitcnt lgkmcnt(0)
	s_barrier
	ds_read_b32 v0, v0
	s_mov_b64 s[36:37], -1
	s_waitcnt lgkmcnt(0)
	v_cmp_le_i32_e32 vcc, s15, v0
	v_readfirstlane_b32 s18, v0
	s_cbranch_vccnz .LBB0_636
	v_readlane_b32 s100, v254, 0
	s_nop 3
	s_mul_i32 s101, s100, 0x44
	s_addk_i32 s101, 0x348
	s_lshl_b32 s19, s100, 4
	s_add_i32 s42, s19, 0x2d8
	s_cmpk_lt_u32 s18, 0x78
	s_cselect_b32 s101, s42, s101
	s_add_i32 s42, s19, 0x268
	s_cmpk_lt_u32 s18, 0x68
	s_cselect_b32 s101, s42, s101
	s_add_i32 s42, s19, 0x1f8
	s_cmpk_lt_u32 s18, 0x58
	s_cselect_b32 s101, s42, s101
	s_lshl_b32 s42, s100, 5
	s_addk_i32 s42, 0x118
	s_cmpk_lt_u32 s18, 0x48
	s_cselect_b32 s101, s42, s101
	s_add_i32 s42, s19, 0xa8
	s_cmpk_lt_u32 s18, 0x28
	s_cselect_b32 s101, s42, s101
	s_add_i32 s42, s19, 56
	s_cmpk_lt_u32 s18, 0x18
	s_cselect_b32 s101, s42, s101
	s_lshl_b32 s42, s100, 3
	s_cmpk_lt_u32 s18, 8
	s_cselect_b32 s101, s42, s101
	s_add_i32 s18, s18, s101
	s_cmp_gt_i32 s18, 63
	s_cbranch_scc0 .LBB0_840
	s_lshl_b32 s42, s18, 1
	v_readlane_b32 s19, v251, 54
	s_add_i32 s19, s19, s42
	s_cmpk_gt_i32 s19, 0xff
	s_cbranch_scc0 .LBB0_775
	s_cmpk_gt_u32 s19, 0x1ff
	s_cbranch_scc0 .LBB0_751
	s_cmpk_gt_u32 s19, 0x3ff
	s_cbranch_scc0 .LBB0_704
	s_cmpk_gt_u32 s19, 0x4ff
	s_cbranch_scc0 .LBB0_696
	s_cmpk_gt_u32 s19, 0x5ff
	s_cbranch_scc0 .LBB0_673
	s_cmpk_gt_u32 s19, 0x6ff
	s_cbranch_scc0 .LBB0_654
	s_cmpk_gt_u32 s19, 0xa3f
	s_cbranch_scc0 .LBB0_651
	s_lshl_b32 s20, s19, 3
	s_and_b32 s20, s20, 0x7fffffc0
	s_add_i32 s70, s20, 0xffffae00
	s_lshl_b32 s20, s19, 8
	v_mov_b32_e32 v2, v189
	s_and_b32 s20, s20, 0x700
	s_lshl_b32 s21, s20, 2
	v_ashrrev_i32_e32 v3, 6, v2
	v_readlane_b32 s22, v252, 45
	v_add_u32_e32 v0, s70, v3
	s_add_u32 s22, s22, s21
	v_readlane_b32 s21, v252, 46
	v_lshlrev_b32_e32 v1, 4, v2
	s_addc_u32 s23, s21, 0
	v_and_b32_e32 v160, 0x3f0, v1
	v_ashrrev_i32_e32 v1, 31, v0
	v_lshl_add_u64 v[4:5], s[22:23], 0, v[160:161]
	v_lshlrev_b64 v[0:1], 13, v[0:1]
	v_lshl_add_u64 v[0:1], v[4:5], 0, v[0:1]
	global_load_dwordx4 v[24:27], v[0:1], off
	s_mov_b64 s[100:101], 0x8000
	v_lshl_add_u64 v[4:5], v[0:1], 0, s[100:101]
	global_load_dwordx4 v[28:31], v[4:5], off
	v_lshl_add_u64 v[4:5], v[4:5], 0, s[100:101]
	global_load_dwordx4 v[32:35], v[4:5], off
	v_lshl_add_u64 v[4:5], v[4:5], 0, s[100:101]
	global_load_dwordx4 v[36:39], v[4:5], off
	v_lshl_add_u64 v[4:5], v[4:5], 0, s[100:101]
	global_load_dwordx4 v[40:43], v[4:5], off
	v_lshl_add_u64 v[4:5], v[4:5], 0, s[100:101]
	global_load_dwordx4 v[44:47], v[4:5], off
	v_lshl_add_u64 v[4:5], v[4:5], 0, s[100:101]
	global_load_dwordx4 v[48:51], v[4:5], off
	v_lshl_add_u64 v[4:5], v[4:5], 0, s[100:101]
	global_load_dwordx4 v[52:55], v[4:5], off
	v_lshl_add_u64 v[4:5], v[4:5], 0, s[100:101]
	global_load_dwordx4 v[56:59], v[4:5], off
	v_lshl_add_u64 v[4:5], v[4:5], 0, s[100:101]
	global_load_dwordx4 v[60:63], v[4:5], off
	v_lshl_add_u64 v[4:5], v[4:5], 0, s[100:101]
	global_load_dwordx4 v[64:67], v[4:5], off
	v_lshl_add_u64 v[4:5], v[4:5], 0, s[100:101]
	global_load_dwordx4 v[68:71], v[4:5], off
	v_lshl_add_u64 v[4:5], v[4:5], 0, s[100:101]
	global_load_dwordx4 v[72:75], v[4:5], off
	v_lshl_add_u64 v[4:5], v[4:5], 0, s[100:101]
	global_load_dwordx4 v[76:79], v[4:5], off
	v_lshl_add_u64 v[4:5], v[4:5], 0, s[100:101]
	global_load_dwordx4 v[80:83], v[4:5], off
	v_lshl_add_u64 v[4:5], v[4:5], 0, s[100:101]
	global_load_dwordx4 v[84:87], v[4:5], off
	s_movk_i32 s36, 0x404
	v_mul_lo_u32 v3, v3, s36
	v_add3_u32 v3, s17, v160, v3
	s_lshl_b64 s[22:23], s[70:71], 1
	v_readlane_b32 s21, v252, 47
	s_nop 0
	s_add_u32 s22, s21, s22
	v_readlane_b32 s21, v252, 48
	s_nop 0
	s_addc_u32 s23, s21, s23
	s_waitcnt vmcnt(15)
	ds_write2_b32 v3, v24, v25 offset1:1
	ds_write2_b32 v3, v26, v27 offset0:2 offset1:3
	s_waitcnt vmcnt(14)
	v_add_u32_e32 v8, 0x1010, v3
	ds_write2_b32 v8, v28, v29 offset1:1
	ds_write2_b32 v8, v30, v31 offset0:2 offset1:3
	s_waitcnt vmcnt(13)
	v_add_u32_e32 v8, 0x2020, v3
	ds_write2_b32 v8, v32, v33 offset1:1
	ds_write2_b32 v8, v34, v35 offset0:2 offset1:3
	s_waitcnt vmcnt(12)
	v_add_u32_e32 v8, 0x3030, v3
	ds_write2_b32 v8, v36, v37 offset1:1
	ds_write2_b32 v8, v38, v39 offset0:2 offset1:3
	s_waitcnt vmcnt(11)
	v_add_u32_e32 v8, 0x4040, v3
	ds_write2_b32 v8, v40, v41 offset1:1
	ds_write2_b32 v8, v42, v43 offset0:2 offset1:3
	s_waitcnt vmcnt(10)
	v_add_u32_e32 v8, 0x5050, v3
	ds_write2_b32 v8, v44, v45 offset1:1
	ds_write2_b32 v8, v46, v47 offset0:2 offset1:3
	s_waitcnt vmcnt(9)
	v_add_u32_e32 v8, 0x6060, v3
	ds_write2_b32 v8, v48, v49 offset1:1
	ds_write2_b32 v8, v50, v51 offset0:2 offset1:3
	s_waitcnt vmcnt(8)
	v_add_u32_e32 v8, 0x7070, v3
	ds_write2_b32 v8, v52, v53 offset1:1
	ds_write2_b32 v8, v54, v55 offset0:2 offset1:3
	s_waitcnt vmcnt(7)
	v_add_u32_e32 v8, 0x8080, v3
	ds_write2_b32 v8, v56, v57 offset1:1
	ds_write2_b32 v8, v58, v59 offset0:2 offset1:3
	s_waitcnt vmcnt(6)
	v_add_u32_e32 v8, 0x9090, v3
	ds_write2_b32 v8, v60, v61 offset1:1
	ds_write2_b32 v8, v62, v63 offset0:2 offset1:3
	s_waitcnt vmcnt(5)
	v_add_u32_e32 v8, 0xa0a0, v3
	ds_write2_b32 v8, v64, v65 offset1:1
	ds_write2_b32 v8, v66, v67 offset0:2 offset1:3
	s_waitcnt vmcnt(4)
	v_add_u32_e32 v8, 0xb0b0, v3
	ds_write2_b32 v8, v68, v69 offset1:1
	ds_write2_b32 v8, v70, v71 offset0:2 offset1:3
	s_waitcnt vmcnt(3)
	v_add_u32_e32 v8, 0xc0c0, v3
	ds_write2_b32 v8, v72, v73 offset1:1
	ds_write2_b32 v8, v74, v75 offset0:2 offset1:3
	s_waitcnt vmcnt(2)
	v_add_u32_e32 v8, 0xd0d0, v3
	ds_write2_b32 v8, v76, v77 offset1:1
	ds_write2_b32 v8, v78, v79 offset0:2 offset1:3
	s_waitcnt vmcnt(1)
	v_add_u32_e32 v8, 0xe0e0, v3
	ds_write2_b32 v8, v80, v81 offset1:1
	ds_write2_b32 v8, v82, v83 offset0:2 offset1:3
	s_waitcnt vmcnt(0)
	v_add_u32_e32 v8, 0xf0f0, v3
	ds_write2_b32 v8, v84, v85 offset1:1
	ds_write2_b32 v8, v86, v87 offset0:2 offset1:3
	v_lshlrev_b32_e32 v0, 3, v2
	v_and_b32_e32 v3, 56, v0
	v_mov_b32_e32 v4, s17
	v_lshlrev_b32_e32 v160, 1, v3
	v_ashrrev_i32_e32 v8, 3, v2
	v_mad_u32_u24 v3, v3, s36, v4
	v_lshl_add_u32 v4, v8, 2, v3
	s_waitcnt lgkmcnt(0)
	s_barrier
	ds_read_b32 v5, v4
	ds_read_b32 v6, v4 offset:1028
	ds_read_b32 v7, v4 offset:2056
	ds_read_b32 v9, v4 offset:3084
	ds_read_b32 v10, v4 offset:4112
	ds_read_b32 v11, v4 offset:5140
	ds_read_b32 v12, v4 offset:6168
	ds_read_b32 v4, v4 offset:7196
	s_waitcnt lgkmcnt(4)
	v_bfe_u32 v20, v5, 16, 1
	v_add3_u32 v20, v5, v20, s94
	v_cvt_pk_bf16_f32 v9, v7, v9
	v_add_u32_e32 v8, s20, v8
	s_waitcnt lgkmcnt(0)
	v_bfe_u32 v19, v6, 16, 1
	v_mov_b32_e32 v5, v9
	v_ashrrev_i32_e32 v9, 31, v8
	v_lshl_add_u64 v[0:1], s[22:23], 0, v[160:161]
	v_add3_u32 v19, v6, v19, s94
	v_cvt_pk_bf16_f32 v10, v10, v11
	v_cvt_pk_bf16_f32 v4, v12, v4
	v_lshlrev_b64 v[8:9], 12, v[8:9]
	v_mov_b32_e32 v7, v4
	v_mov_b32_e32 v6, v10
	v_perm_b32 v4, v19, v20, s95
	v_lshl_add_u64 v[8:9], v[0:1], 0, v[8:9]
	global_store_dwordx4 v[8:9], v[4:7], off
	s_mov_b64 s[36:37], 0
	s_nop 0
	v_add_u32_e32 v4, 0x100, v2
	v_ashrrev_i32_e32 v8, 3, v4
	v_lshl_add_u32 v4, v8, 2, v3
	ds_read_b32 v5, v4
	ds_read_b32 v6, v4 offset:1028
	ds_read_b32 v7, v4 offset:2056
	ds_read_b32 v9, v4 offset:3084
	ds_read_b32 v10, v4 offset:4112
	ds_read_b32 v11, v4 offset:5140
	ds_read_b32 v12, v4 offset:6168
	ds_read_b32 v4, v4 offset:7196
	s_waitcnt lgkmcnt(4)
	v_bfe_u32 v20, v5, 16, 1
	v_add3_u32 v20, v5, v20, s94
	v_cvt_pk_bf16_f32 v9, v7, v9
	v_add_u32_e32 v8, s20, v8
	s_waitcnt lgkmcnt(0)
	v_bfe_u32 v19, v6, 16, 1
	v_mov_b32_e32 v5, v9
	v_ashrrev_i32_e32 v9, 31, v8
	v_add3_u32 v19, v6, v19, s94
	v_cvt_pk_bf16_f32 v10, v10, v11
	v_cvt_pk_bf16_f32 v4, v12, v4
	v_lshlrev_b64 v[8:9], 12, v[8:9]
	v_mov_b32_e32 v7, v4
	v_mov_b32_e32 v6, v10
	v_perm_b32 v4, v19, v20, s95
	v_lshl_add_u64 v[8:9], v[0:1], 0, v[8:9]
	global_store_dwordx4 v[8:9], v[4:7], off
	s_nop 1
	v_add_u32_e32 v4, 0x200, v2
	v_ashrrev_i32_e32 v8, 3, v4
	v_lshl_add_u32 v4, v8, 2, v3
	ds_read_b32 v5, v4
	ds_read_b32 v6, v4 offset:1028
	ds_read_b32 v7, v4 offset:2056
	ds_read_b32 v9, v4 offset:3084
	ds_read_b32 v10, v4 offset:4112
	ds_read_b32 v11, v4 offset:5140
	ds_read_b32 v12, v4 offset:6168
	ds_read_b32 v4, v4 offset:7196
	s_waitcnt lgkmcnt(4)
	v_bfe_u32 v20, v5, 16, 1
	v_add3_u32 v20, v5, v20, s94
	v_cvt_pk_bf16_f32 v9, v7, v9
	v_add_u32_e32 v8, s20, v8
	s_waitcnt lgkmcnt(0)
	v_bfe_u32 v19, v6, 16, 1
	v_mov_b32_e32 v5, v9
	v_ashrrev_i32_e32 v9, 31, v8
	v_add3_u32 v19, v6, v19, s94
	v_cvt_pk_bf16_f32 v10, v10, v11
	v_cvt_pk_bf16_f32 v4, v12, v4
	v_lshlrev_b64 v[8:9], 12, v[8:9]
	v_mov_b32_e32 v7, v4
	v_mov_b32_e32 v6, v10
	v_perm_b32 v4, v19, v20, s95
	v_lshl_add_u64 v[8:9], v[0:1], 0, v[8:9]
	global_store_dwordx4 v[8:9], v[4:7], off
	s_nop 1
	v_add_u32_e32 v4, 0x300, v2
	v_ashrrev_i32_e32 v8, 3, v4
	v_lshl_add_u32 v4, v8, 2, v3
	ds_read_b32 v5, v4
	ds_read_b32 v6, v4 offset:1028
	ds_read_b32 v7, v4 offset:2056
	ds_read_b32 v9, v4 offset:3084
	ds_read_b32 v10, v4 offset:4112
	ds_read_b32 v11, v4 offset:5140
	ds_read_b32 v12, v4 offset:6168
	ds_read_b32 v4, v4 offset:7196
	s_waitcnt lgkmcnt(4)
	v_bfe_u32 v20, v5, 16, 1
	v_add3_u32 v20, v5, v20, s94
	v_cvt_pk_bf16_f32 v9, v7, v9
	v_add_u32_e32 v8, s20, v8
	s_waitcnt lgkmcnt(0)
	v_bfe_u32 v19, v6, 16, 1
	v_mov_b32_e32 v5, v9
	v_ashrrev_i32_e32 v9, 31, v8
	v_add3_u32 v19, v6, v19, s94
	v_cvt_pk_bf16_f32 v10, v10, v11
	v_cvt_pk_bf16_f32 v4, v12, v4
	v_lshlrev_b64 v[8:9], 12, v[8:9]
	v_mov_b32_e32 v7, v4
	v_mov_b32_e32 v6, v10
	v_perm_b32 v4, v19, v20, s95
	v_lshl_add_u64 v[8:9], v[0:1], 0, v[8:9]
	global_store_dwordx4 v[8:9], v[4:7], off
	s_nop 1
	v_add_u32_e32 v4, 0x400, v2
	v_ashrrev_i32_e32 v8, 3, v4
	v_lshl_add_u32 v4, v8, 2, v3
	ds_read_b32 v5, v4
	ds_read_b32 v6, v4 offset:1028
	ds_read_b32 v7, v4 offset:2056
	ds_read_b32 v9, v4 offset:3084
	ds_read_b32 v10, v4 offset:4112
	ds_read_b32 v11, v4 offset:5140
	ds_read_b32 v12, v4 offset:6168
	ds_read_b32 v4, v4 offset:7196
	s_waitcnt lgkmcnt(4)
	v_bfe_u32 v20, v5, 16, 1
	v_add3_u32 v20, v5, v20, s94
	v_cvt_pk_bf16_f32 v9, v7, v9
	v_add_u32_e32 v8, s20, v8
	s_waitcnt lgkmcnt(0)
	v_bfe_u32 v19, v6, 16, 1
	v_mov_b32_e32 v5, v9
	v_ashrrev_i32_e32 v9, 31, v8
	v_add3_u32 v19, v6, v19, s94
	v_cvt_pk_bf16_f32 v10, v10, v11
	v_cvt_pk_bf16_f32 v4, v12, v4
	v_lshlrev_b64 v[8:9], 12, v[8:9]
	v_mov_b32_e32 v7, v4
	v_mov_b32_e32 v6, v10
	v_perm_b32 v4, v19, v20, s95
	v_lshl_add_u64 v[8:9], v[0:1], 0, v[8:9]
	global_store_dwordx4 v[8:9], v[4:7], off
	s_nop 1
	v_add_u32_e32 v4, 0x500, v2
	v_ashrrev_i32_e32 v8, 3, v4
	v_lshl_add_u32 v4, v8, 2, v3
	ds_read_b32 v5, v4
	ds_read_b32 v6, v4 offset:1028
	ds_read_b32 v7, v4 offset:2056
	ds_read_b32 v9, v4 offset:3084
	ds_read_b32 v10, v4 offset:4112
	ds_read_b32 v11, v4 offset:5140
	ds_read_b32 v12, v4 offset:6168
	ds_read_b32 v4, v4 offset:7196
	s_waitcnt lgkmcnt(4)
	v_bfe_u32 v20, v5, 16, 1
	v_add3_u32 v20, v5, v20, s94
	v_cvt_pk_bf16_f32 v9, v7, v9
	v_add_u32_e32 v8, s20, v8
	s_waitcnt lgkmcnt(0)
	v_bfe_u32 v19, v6, 16, 1
	v_mov_b32_e32 v5, v9
	v_ashrrev_i32_e32 v9, 31, v8
	v_add3_u32 v19, v6, v19, s94
	v_cvt_pk_bf16_f32 v10, v10, v11
	v_cvt_pk_bf16_f32 v4, v12, v4
	v_lshlrev_b64 v[8:9], 12, v[8:9]
	v_mov_b32_e32 v7, v4
	v_mov_b32_e32 v6, v10
	v_perm_b32 v4, v19, v20, s95
	v_lshl_add_u64 v[8:9], v[0:1], 0, v[8:9]
	global_store_dwordx4 v[8:9], v[4:7], off
	s_nop 1
	v_add_u32_e32 v4, 0x600, v2
	v_ashrrev_i32_e32 v8, 3, v4
	v_lshl_add_u32 v4, v8, 2, v3
	ds_read_b32 v5, v4
	ds_read_b32 v6, v4 offset:1028
	ds_read_b32 v7, v4 offset:2056
	ds_read_b32 v9, v4 offset:3084
	ds_read_b32 v10, v4 offset:4112
	ds_read_b32 v11, v4 offset:5140
	ds_read_b32 v12, v4 offset:6168
	ds_read_b32 v4, v4 offset:7196
	s_waitcnt lgkmcnt(4)
	v_bfe_u32 v20, v5, 16, 1
	v_add3_u32 v20, v5, v20, s94
	v_cvt_pk_bf16_f32 v9, v7, v9
	v_add_u32_e32 v8, s20, v8
	s_waitcnt lgkmcnt(0)
	v_bfe_u32 v19, v6, 16, 1
	v_mov_b32_e32 v5, v9
	v_ashrrev_i32_e32 v9, 31, v8
	v_add3_u32 v19, v6, v19, s94
	v_cvt_pk_bf16_f32 v10, v10, v11
	v_cvt_pk_bf16_f32 v4, v12, v4
	v_lshlrev_b64 v[8:9], 12, v[8:9]
	v_mov_b32_e32 v7, v4
	v_mov_b32_e32 v6, v10
	v_perm_b32 v4, v19, v20, s95
	v_lshl_add_u64 v[8:9], v[0:1], 0, v[8:9]
	v_add_u32_e32 v2, 0x700, v2
	global_store_dwordx4 v[8:9], v[4:7], off
	s_nop 1
	v_ashrrev_i32_e32 v6, 3, v2
	v_lshl_add_u32 v2, v6, 2, v3
	ds_read_b32 v3, v2
	ds_read_b32 v4, v2 offset:1028
	ds_read_b32 v5, v2 offset:2056
	ds_read_b32 v7, v2 offset:3084
	ds_read_b32 v8, v2 offset:4112
	ds_read_b32 v9, v2 offset:5140
	ds_read_b32 v10, v2 offset:6168
	ds_read_b32 v2, v2 offset:7196
	s_waitcnt lgkmcnt(4)
	v_bfe_u32 v18, v3, 16, 1
	v_add3_u32 v18, v3, v18, s94
	v_cvt_pk_bf16_f32 v7, v5, v7
	v_add_u32_e32 v6, s20, v6
	s_waitcnt lgkmcnt(0)
	v_bfe_u32 v17, v4, 16, 1
	v_mov_b32_e32 v3, v7
	v_ashrrev_i32_e32 v7, 31, v6
	v_add3_u32 v17, v4, v17, s94
	v_cvt_pk_bf16_f32 v8, v8, v9
	v_cvt_pk_bf16_f32 v2, v10, v2
	v_lshlrev_b64 v[6:7], 12, v[6:7]
	v_mov_b32_e32 v5, v2
	v_mov_b32_e32 v4, v8
	v_perm_b32 v2, v17, v18, s95
	v_lshl_add_u64 v[0:1], v[0:1], 0, v[6:7]
	global_store_dwordx4 v[0:1], v[2:5], off
	s_barrier
